# attention DMA loop: one static s_setprio 1 for waves 4-7 per unit
# speedup vs baseline: 1.0003x; 1.0003x over previous
; #define AT_LOAD(X, t) do { const size_t adv_ = (size_t)(t) * 64; sk##X = *(const u32x4*)(gk + adv_ * 1024); sv##X = *(const u32x4*)(gv + adv_ * 1024); if (rth) sr##X = *(const u32x4*)(gr + adv_ * 32); } while (0)
; #define AT_STORE(X, slot) do { *(LAS u32x4*)(lds + A_K0 + (slot) * AK_BYTES + lk) = sk##X; *(LAS u32x4*)(lds + A_V0 + (slot) * AV_BYTES + lv) = sv##X; if (rth) *(LAS u32x4*)(lds + A_K0 + (slot) * AK_BYTES + lr) = sr##X; } while (0)
; __device__ __forceinline__ void attn_unit(LAS char* lds, const bf16_t* Qp, const bf16_t* KVp, const bf16_t* KRp, int ntiles, bf16_t* Yp, bool dry) {
;     ...
;     const int krow = tid >> 3, kc = tid & 7, rrow = tid >> 2, rc = tid & 3;
;     const bf16_t* gk = KVp + (size_t)krow * 1024 + kc * 8;
;     const bf16_t* gv = gk + 512;
;     const bf16_t* gr = KRp + (size_t)rrow * 32 + rc * 8;
;     const int lk = krow * AK_PITCH + kc * 16, lr = rrow * AK_PITCH + 128 + rc * 16, lv = (kc >> 2) * 4096 + krow * 64 + (kc & 3) * 16;
;     const bool rth = tid < 256;
;     u32x4 skA, svA, srA = {0u, 0u, 0u, 0u}, skB, svB, srB = {0u, 0u, 0u, 0u};
;     ...
;     for (int t = 0; t < ntiles; t += 2) {
;         const int sb0 = (t & 2);
;         const bool more = (t + 2 < ntiles);
;         f32x16 pa0 = {}, pa1 = {}, pb0 = {}, pb1 = {};
;         AT_QK(sb0, pa0, pa1);
;         AT_QK(sb0 + 1, pb0, pb1);
;         if (t == 0) AT_SMPV(sb0, true, pa0, pa1); else AT_SMPV(sb0, false, pa0, pa1);
;         __builtin_amdgcn_sched_barrier(0);
;         if (more) { AT_LOAD(A, t + 2); AT_LOAD(B, t + 3); }
;         AT_SMPV(sb0 + 1, false, pb0, pb1);
;         if (more) { AT_STORE(A, sb0 ^ 2); AT_STORE(B, (sb0 ^ 2) + 1); }
.Latt_iter:
	s_waitcnt vmcnt(0)
	v_xor_b32_e32 v82, 0x80000000, v189
	v_mov_b32_e32 v83, v82
	v_mov_b32_e32 v84, v82
	v_mov_b32_e32 v85, v82
	v_mov_b32_e32 v86, v82
	v_mov_b32_e32 v87, v82
	v_mov_b32_e32 v88, v82
	v_mov_b32_e32 v89, v82
	v_mov_b32_e32 v90, v82
	v_mov_b32_e32 v91, v82
	v_mov_b32_e32 v92, v82
	v_mov_b32_e32 v93, v82
	v_mov_b32_e32 v94, v82
	v_mov_b32_e32 v95, v82
	v_mov_b32_e32 v96, v82
	v_mov_b32_e32 v97, v82
	s_ashr_i32 s14, s8, 6
	s_mul_i32 s2, s14, 0x480000
	s_bfe_u32 s15, s8, 0x30003
	s_lshl_b32 s15, s15, 7
	s_add_i32 s2, s2, s15
	s_add_u32 s2, s2, 0x2f440000
	s_add_u32 s2, s88, s2
	s_addc_u32 s3, s89, 0
	s_mul_i32 s16, s14, 0x24000
	s_add_u32 s16, s16, 0x3cc02000
	s_add_u32 s16, s88, s16
	s_addc_u32 s17, s89, 0
	v_mov_b32_e32 v180, 0x40000
	v_mov_b32_e32 v181, 0x2000
	v_mov_b32_e32 v146, v182
	v_cmp_lt_u32_e32 vcc, 831, v146
	v_cndmask_b32_e64 v147, 0, 1, vcc
	v_mul_u32_u24_e32 v148, 832, v147
	v_sub_u32_e32 v146, v146, v148
	v_mul_u32_u24_e32 v148, 5042, v146
	v_lshrrev_b32_e32 v148, 16, v148
	v_mul_u32_u24_e32 v149, 13, v148
	v_sub_u32_e32 v149, v146, v149
	v_cmp_eq_u32_e32 vcc, 12, v149
	v_cndmask_b32_e64 v149, v149, 0, vcc
	v_lshlrev_b32_e32 v150, 17, v147
	v_lshl_add_u32 v150, v148, 11, v150
	v_lshl_add_u32 v150, v149, 4, v150
	v_lshlrev_b32_e32 v151, 12, v147
	v_lshl_add_u32 v151, v148, 6, v151
	v_lshl_add_u32 v151, v149, 4, v151
	v_add_u32_e32 v151, 0xffffff80, v151
	v_cmp_lt_u32_e64 s[14:15], 7, v149
	v_cndmask_b32_e64 v150, v150, v151, s[14:15]
	v_mov_b32_e32 v152, s2
	v_mov_b32_e32 v153, s3
	v_mov_b32_e32 v178, s16
	v_mov_b32_e32 v179, s17
	v_cndmask_b32_e64 v152, v152, v178, s[14:15]
	v_cndmask_b32_e64 v153, v153, v179, s[14:15]
	v_cndmask_b32_e64 v142, v180, v181, s[14:15]
	v_add_co_u32_e32 v130, vcc, v150, v152
	s_nop 1
	v_addc_co_u32_e32 v131, vcc, 0, v153, vcc
	v_add_u32_e32 v146, 512, v182
	v_cmp_lt_u32_e32 vcc, 831, v146
	v_cndmask_b32_e64 v147, 0, 1, vcc
	v_mul_u32_u24_e32 v148, 832, v147
	v_sub_u32_e32 v146, v146, v148
	v_mul_u32_u24_e32 v148, 5042, v146
	v_lshrrev_b32_e32 v148, 16, v148
	v_mul_u32_u24_e32 v149, 13, v148
	v_sub_u32_e32 v149, v146, v149
	v_cmp_eq_u32_e32 vcc, 12, v149
	v_cndmask_b32_e64 v149, v149, 0, vcc
	v_lshlrev_b32_e32 v150, 17, v147
	v_lshl_add_u32 v150, v148, 11, v150
	v_lshl_add_u32 v150, v149, 4, v150
	v_lshlrev_b32_e32 v151, 12, v147
	v_lshl_add_u32 v151, v148, 6, v151
	v_lshl_add_u32 v151, v149, 4, v151
	v_add_u32_e32 v151, 0xffffff80, v151
	v_cmp_lt_u32_e64 s[14:15], 7, v149
	v_cndmask_b32_e64 v150, v150, v151, s[14:15]
	v_mov_b32_e32 v152, s2
	v_mov_b32_e32 v153, s3
	v_mov_b32_e32 v178, s16
	v_mov_b32_e32 v179, s17
	v_cndmask_b32_e64 v152, v152, v178, s[14:15]
	v_cndmask_b32_e64 v153, v153, v179, s[14:15]
	v_cndmask_b32_e64 v143, v180, v181, s[14:15]
	v_add_co_u32_e32 v132, vcc, v150, v152
	s_nop 1
	v_addc_co_u32_e32 v133, vcc, 0, v153, vcc
	v_add_u32_e32 v146, 1024, v182
	v_cmp_lt_u32_e32 vcc, 831, v146
	v_cndmask_b32_e64 v147, 0, 1, vcc
	v_mul_u32_u24_e32 v148, 832, v147
	v_sub_u32_e32 v146, v146, v148
	v_mul_u32_u24_e32 v148, 5042, v146
	v_lshrrev_b32_e32 v148, 16, v148
	v_mul_u32_u24_e32 v149, 13, v148
	v_sub_u32_e32 v149, v146, v149
	v_cmp_eq_u32_e32 vcc, 12, v149
	v_cndmask_b32_e64 v149, v149, 0, vcc
	v_lshlrev_b32_e32 v150, 17, v147
	v_lshl_add_u32 v150, v148, 11, v150
	v_lshl_add_u32 v150, v149, 4, v150
	v_lshlrev_b32_e32 v151, 12, v147
	v_lshl_add_u32 v151, v148, 6, v151
	v_lshl_add_u32 v151, v149, 4, v151
	v_add_u32_e32 v151, 0xffffff80, v151
	v_cmp_lt_u32_e64 s[14:15], 7, v149
	v_cndmask_b32_e64 v150, v150, v151, s[14:15]
	v_mov_b32_e32 v152, s2
	v_mov_b32_e32 v153, s3
	v_mov_b32_e32 v178, s16
	v_mov_b32_e32 v179, s17
	v_cndmask_b32_e64 v152, v152, v178, s[14:15]
	v_cndmask_b32_e64 v153, v153, v179, s[14:15]
	v_cndmask_b32_e64 v144, v180, v181, s[14:15]
	v_add_co_u32_e32 v134, vcc, v150, v152
	s_nop 1
	v_addc_co_u32_e32 v135, vcc, 0, v153, vcc
	v_add_u32_e32 v146, 1536, v182
	v_cmp_lt_u32_e32 vcc, 831, v146
	v_cndmask_b32_e64 v147, 0, 1, vcc
	v_mul_u32_u24_e32 v148, 832, v147
	v_sub_u32_e32 v146, v146, v148
	v_mul_u32_u24_e32 v148, 5042, v146
	v_lshrrev_b32_e32 v148, 16, v148
	v_mul_u32_u24_e32 v149, 13, v148
	v_sub_u32_e32 v149, v146, v149
	v_cmp_eq_u32_e32 vcc, 12, v149
	v_cndmask_b32_e64 v149, v149, 0, vcc
	v_lshlrev_b32_e32 v150, 17, v147
	v_lshl_add_u32 v150, v148, 11, v150
	v_lshl_add_u32 v150, v149, 4, v150
	v_lshlrev_b32_e32 v151, 12, v147
	v_lshl_add_u32 v151, v148, 6, v151
	v_lshl_add_u32 v151, v149, 4, v151
	v_add_u32_e32 v151, 0xffffff80, v151
	v_cmp_lt_u32_e64 s[14:15], 7, v149
	v_cndmask_b32_e64 v150, v150, v151, s[14:15]
	v_mov_b32_e32 v152, s2
	v_mov_b32_e32 v153, s3
	v_mov_b32_e32 v178, s16
	v_mov_b32_e32 v179, s17
	v_cndmask_b32_e64 v152, v152, v178, s[14:15]
	v_cndmask_b32_e64 v153, v153, v179, s[14:15]
	v_cndmask_b32_e64 v145, v180, v181, s[14:15]
	v_add_co_u32_e32 v136, vcc, v150, v152
	s_nop 1
	v_addc_co_u32_e32 v137, vcc, 0, v153, vcc
	v_bfe_u32 v146, v182, 6, 2
	v_bfe_u32 v147, v182, 2, 4
	v_lshl_add_u32 v146, v146, 4, v147
	v_bfe_u32 v147, v182, 8, 1
	v_and_b32_e32 v148, 3, v182
	v_lshl_add_u32 v147, v147, 2, v148
	v_lshlrev_b32_e32 v146, 11, v146
	v_lshl_add_u32 v146, v147, 4, v146
	v_add_u32_e32 v146, 0x400, v146
	v_mov_b32_e32 v147, s3
	v_add_co_u32_e32 v138, vcc, s2, v146
	s_nop 1
	v_addc_co_u32_e32 v139, vcc, 0, v147, vcc
	v_add_co_u32_e32 v140, vcc, 0x20000, v138
	s_nop 1
	v_addc_co_u32_e32 v141, vcc, 0, v139, vcc
	s_cmp_lt_u32 s29, 4
	s_cbranch_scc1 .Latt_noprio
	s_setprio 1
.Latt_noprio:
.Latt_loop:
	s_and_b32 s42, s35, 2
	s_mul_i32 s2, s42, 0x3400
	v_add_u32_e32 v0, s2, v209
	v_lshl_add_u32 v185, s42, 13, v208
	v_add_u32_e32 v184, 0x2000, v185
	s_cmp_gt_u32 s35, 33
	s_cbranch_scc1 .Latt_noload
	s_xor_b32 s14, s42, 2
	s_mul_i32 s15, s14, 0x3400
	s_lshl_b32 s16, s29, 10
	s_add_i32 s15, s15, s16
	s_mov_b32 m0, s15
	s_add_i32 s15, s15, 0x2000
	global_load_lds_dwordx4 v[130:131], off
	s_mov_b32 m0, s15
	s_add_i32 s15, s15, 0x2000
	global_load_lds_dwordx4 v[132:133], off
	s_mov_b32 m0, s15
	s_add_i32 s15, s15, 0x2000
	global_load_lds_dwordx4 v[134:135], off
	s_cmp_gt_u32 s29, 1
	s_cbranch_scc1 .Latt_dk3
	s_mov_b32 m0, s15
	s_nop 0
	global_load_lds_dwordx4 v[136:137], off

; #define AT_LOAD(X, t) do { const size_t adv_ = (size_t)(t) * 64; sk##X = *(const u32x4*)(gk + adv_ * 1024); sv##X = *(const u32x4*)(gv + adv_ * 1024); if (rth) sr##X = *(const u32x4*)(gr + adv_ * 32); } while (0)
; #define AT_STORE(X, slot) do { *(LAS u32x4*)(lds + A_K0 + (slot) * AK_BYTES + lk) = sk##X; *(LAS u32x4*)(lds + A_V0 + (slot) * AV_BYTES + lv) = sv##X; if (rth) *(LAS u32x4*)(lds + A_K0 + (slot) * AK_BYTES + lr) = sr##X; } while (0)
; __device__ __forceinline__ void attn_unit(LAS char* lds, const bf16_t* Qp, const bf16_t* KVp, const bf16_t* KRp, int ntiles, bf16_t* Yp, bool dry) {
;     ...
;     for (int t = 0; t < ntiles; t += 2) {
;         const int sb0 = (t & 2);
;         const bool more = (t + 2 < ntiles);
;         f32x16 pa0 = {}, pa1 = {}, pb0 = {}, pb1 = {};
;         AT_QK(sb0, pa0, pa1);
;         AT_QK(sb0 + 1, pb0, pb1);
;         if (t == 0) AT_SMPV(sb0, true, pa0, pa1); else AT_SMPV(sb0, false, pa0, pa1);
;         __builtin_amdgcn_sched_barrier(0);
;         if (more) { AT_LOAD(A, t + 2); AT_LOAD(B, t + 3); }
;         AT_SMPV(sb0 + 1, false, pb0, pb1);
;         if (more) { AT_STORE(A, sb0 ^ 2); AT_STORE(B, (sb0 ^ 2) + 1); }
;         __syncthreads();
;     }
;     ...
;     lsum += __shfl_xor(lsum, 32);
.Latt_nw:
	s_add_i32 s35, s35, 2
	s_waitcnt lgkmcnt(0)
	s_barrier
	s_cmp_lt_u32 s35, 36
	s_cbranch_scc1 .Latt_loop
	s_setprio 0
	v_and_b32_e32 v3, 64, v203
	v_xor_b32_e32 v2, 32, v203
	v_add_u32_e32 v3, 64, v3
	v_cmp_lt_i32_e32 vcc, v2, v3
	s_nop 1
	v_cndmask_b32_e32 v2, v203, v2, vcc
	v_lshlrev_b32_e32 v98, 2, v2
	s_branch .LBB0_858
